# a1 top-k bisection: count blocks rewritten as VOP3 compares into rotating SGPR pairs + addc (no hazard nops), on top of sp4 select fix and nt proj stores
# speedup vs baseline: 1.1739x; 1.0021x over previous
; DI void a1_task(unsigned char* shm, const bf16_t* prm, const bf16_t* prt, unsigned* mask, int b, int qt, const int tid) {
;     ...
;             const unsigned cand = T | (1u << bit);
;             int c = 0;
; #pragma unroll
;             for (int jt = 0; jt < 8; ++jt) {
;                 if (jt < nheld) {
; #pragma unroll
;                     for (int i = 0; i < 16; ++i) c += (key[jt][i] >= cand) ? 1 : 0;
;                 }
;             }
.LBB0_461:
	v_lshlrev_b32_e64 v18, v2, 1
	v_or_b32_e32 v18, v0, v18
	s_andn2_b64 vcc, exec, s[38:39]
	v_mov_b32_e32 v19, 0
	s_cbranch_vccnz .LBB0_469
	v_cmp_ge_u32_e64 s[0:1], v141, v18
	v_cmp_ge_u32_e64 s[54:55], v142, v18
	v_cmp_ge_u32_e64 s[98:99], v144, v18
	v_cmp_ge_u32_e64 s[22:23], v143, v18
	v_addc_co_u32_e64 v19, vcc, 0, v19, s[0:1]
	v_cmp_ge_u32_e64 s[0:1], v146, v18
	v_addc_co_u32_e64 v19, vcc, 0, v19, s[54:55]
	v_cmp_ge_u32_e64 s[54:55], v145, v18
	v_addc_co_u32_e64 v19, vcc, 0, v19, s[98:99]
	v_cmp_ge_u32_e64 s[98:99], v149, v18
	v_addc_co_u32_e64 v19, vcc, 0, v19, s[22:23]
	v_cmp_ge_u32_e64 s[22:23], v147, v18
	v_addc_co_u32_e64 v19, vcc, 0, v19, s[0:1]
	v_cmp_ge_u32_e64 s[0:1], v151, v18
	v_addc_co_u32_e64 v19, vcc, 0, v19, s[54:55]
	v_cmp_ge_u32_e64 s[54:55], v150, v18
	v_addc_co_u32_e64 v19, vcc, 0, v19, s[98:99]
	v_cmp_ge_u32_e64 s[98:99], v153, v18
	v_addc_co_u32_e64 v19, vcc, 0, v19, s[22:23]
	v_cmp_ge_u32_e64 s[22:23], v152, v18
	v_addc_co_u32_e64 v19, vcc, 0, v19, s[0:1]
	v_cmp_ge_u32_e64 s[0:1], v155, v18
	v_addc_co_u32_e64 v19, vcc, 0, v19, s[54:55]
	v_cmp_ge_u32_e64 s[54:55], v154, v18
	v_addc_co_u32_e64 v19, vcc, 0, v19, s[98:99]
	v_cmp_ge_u32_e64 s[98:99], v157, v18
	v_addc_co_u32_e64 v19, vcc, 0, v19, s[22:23]
	v_cmp_ge_u32_e64 s[22:23], v156, v18
	v_addc_co_u32_e64 v19, vcc, 0, v19, s[0:1]
	v_addc_co_u32_e64 v19, vcc, 0, v19, s[54:55]
	v_addc_co_u32_e64 v19, vcc, 0, v19, s[98:99]
	v_addc_co_u32_e64 v19, vcc, 0, v19, s[22:23]
	s_andn2_b64 vcc, exec, s[6:7]
	s_cbranch_vccz .LBB0_470

; DI void a1_task(unsigned char* shm, const bf16_t* prm, const bf16_t* prt, unsigned* mask, int b, int qt, const int tid) {
;     ...
;             for (int jt = 0; jt < 8; ++jt) {
;                 if (jt < nheld) {
; #pragma unroll
;                     for (int i = 0; i < 16; ++i) c += (key[jt][i] >= cand) ? 1 : 0;
;                 }
.LBB0_464:
	v_cmp_ge_u32_e64 s[0:1], v175, v18
	v_cmp_ge_u32_e64 s[54:55], v177, v18
	v_cmp_ge_u32_e64 s[98:99], v179, v18
	v_cmp_ge_u32_e64 s[22:23], v181, v18
	v_addc_co_u32_e64 v19, vcc, 0, v19, s[0:1]
	v_cmp_ge_u32_e64 s[0:1], v183, v18
	v_addc_co_u32_e64 v19, vcc, 0, v19, s[54:55]
	v_cmp_ge_u32_e64 s[54:55], v185, v18
	v_addc_co_u32_e64 v19, vcc, 0, v19, s[98:99]
	v_cmp_ge_u32_e64 s[98:99], v187, v18
	v_addc_co_u32_e64 v19, vcc, 0, v19, s[22:23]
	v_cmp_ge_u32_e64 s[22:23], v189, v18
	v_addc_co_u32_e64 v19, vcc, 0, v19, s[0:1]
	v_cmp_ge_u32_e64 s[0:1], v174, v18
	v_addc_co_u32_e64 v19, vcc, 0, v19, s[54:55]
	v_cmp_ge_u32_e64 s[54:55], v176, v18
	v_addc_co_u32_e64 v19, vcc, 0, v19, s[98:99]
	v_cmp_ge_u32_e64 s[98:99], v178, v18
	v_addc_co_u32_e64 v19, vcc, 0, v19, s[22:23]
	v_cmp_ge_u32_e64 s[22:23], v180, v18
	v_addc_co_u32_e64 v19, vcc, 0, v19, s[0:1]
	v_cmp_ge_u32_e64 s[0:1], v182, v18
	v_addc_co_u32_e64 v19, vcc, 0, v19, s[54:55]
	v_cmp_ge_u32_e64 s[54:55], v184, v18
	v_addc_co_u32_e64 v19, vcc, 0, v19, s[98:99]
	v_cmp_ge_u32_e64 s[98:99], v186, v18
	v_addc_co_u32_e64 v19, vcc, 0, v19, s[22:23]
	v_cmp_ge_u32_e64 s[22:23], v188, v18
	v_addc_co_u32_e64 v19, vcc, 0, v19, s[0:1]
	v_addc_co_u32_e64 v19, vcc, 0, v19, s[54:55]
	v_addc_co_u32_e64 v19, vcc, 0, v19, s[98:99]
	v_addc_co_u32_e64 v19, vcc, 0, v19, s[22:23]
	s_andn2_b64 vcc, exec, s[42:43]
	s_cbranch_vccz .LBB0_472

; DI void a1_task(unsigned char* shm, const bf16_t* prm, const bf16_t* prt, unsigned* mask, int b, int qt, const int tid) {
;     ...
;             for (int jt = 0; jt < 8; ++jt) {
;                 if (jt < nheld) {
; #pragma unroll
;                     for (int i = 0; i < 16; ++i) c += (key[jt][i] >= cand) ? 1 : 0;
;                 }
.LBB0_466:
	v_cmp_ge_u32_e64 s[0:1], v83, v18
	v_cmp_ge_u32_e64 s[54:55], v85, v18
	v_cmp_ge_u32_e64 s[98:99], v91, v18
	v_cmp_ge_u32_e64 s[22:23], v93, v18
	v_addc_co_u32_e64 v19, vcc, 0, v19, s[0:1]
	v_cmp_ge_u32_e64 s[0:1], v224, v18
	v_addc_co_u32_e64 v19, vcc, 0, v19, s[54:55]
	v_cmp_ge_u32_e64 s[54:55], v226, v18
	v_addc_co_u32_e64 v19, vcc, 0, v19, s[98:99]
	v_cmp_ge_u32_e64 s[98:99], v228, v18
	v_addc_co_u32_e64 v19, vcc, 0, v19, s[22:23]
	v_cmp_ge_u32_e64 s[22:23], v230, v18
	v_addc_co_u32_e64 v19, vcc, 0, v19, s[0:1]
	v_cmp_ge_u32_e64 s[0:1], v82, v18
	v_addc_co_u32_e64 v19, vcc, 0, v19, s[54:55]
	v_cmp_ge_u32_e64 s[54:55], v84, v18
	v_addc_co_u32_e64 v19, vcc, 0, v19, s[98:99]
	v_cmp_ge_u32_e64 s[98:99], v90, v18
	v_addc_co_u32_e64 v19, vcc, 0, v19, s[22:23]
	v_cmp_ge_u32_e64 s[22:23], v92, v18
	v_addc_co_u32_e64 v19, vcc, 0, v19, s[0:1]
	v_cmp_ge_u32_e64 s[0:1], v223, v18
	v_addc_co_u32_e64 v19, vcc, 0, v19, s[54:55]
	v_cmp_ge_u32_e64 s[54:55], v225, v18
	v_addc_co_u32_e64 v19, vcc, 0, v19, s[98:99]
	v_cmp_ge_u32_e64 s[98:99], v227, v18
	v_addc_co_u32_e64 v19, vcc, 0, v19, s[22:23]
	v_cmp_ge_u32_e64 s[22:23], v229, v18
	v_addc_co_u32_e64 v19, vcc, 0, v19, s[0:1]
	v_addc_co_u32_e64 v19, vcc, 0, v19, s[54:55]
	v_addc_co_u32_e64 v19, vcc, 0, v19, s[98:99]
	v_addc_co_u32_e64 v19, vcc, 0, v19, s[22:23]
	s_andn2_b64 vcc, exec, s[46:47]
	s_cbranch_vccz .LBB0_474

; DI void a1_task(unsigned char* shm, const bf16_t* prm, const bf16_t* prt, unsigned* mask, int b, int qt, const int tid) {
;     ...
;             for (int jt = 0; jt < 8; ++jt) {
;                 if (jt < nheld) {
; #pragma unroll
;                     for (int i = 0; i < 16; ++i) c += (key[jt][i] >= cand) ? 1 : 0;
;                 }
.LBB0_468:
	v_cmp_ge_u32_e64 s[0:1], v51, v18
	v_cmp_ge_u32_e64 s[54:55], v53, v18
	v_cmp_ge_u32_e64 s[98:99], v55, v18
	v_cmp_ge_u32_e64 s[22:23], v57, v18
	v_addc_co_u32_e64 v19, vcc, 0, v19, s[0:1]
	v_cmp_ge_u32_e64 s[0:1], v59, v18
	v_addc_co_u32_e64 v19, vcc, 0, v19, s[54:55]
	v_cmp_ge_u32_e64 s[54:55], v61, v18
	v_addc_co_u32_e64 v19, vcc, 0, v19, s[98:99]
	v_cmp_ge_u32_e64 s[98:99], v63, v18
	v_addc_co_u32_e64 v19, vcc, 0, v19, s[22:23]
	v_cmp_ge_u32_e64 s[22:23], v65, v18
	v_addc_co_u32_e64 v19, vcc, 0, v19, s[0:1]
	v_cmp_ge_u32_e64 s[0:1], v50, v18
	v_addc_co_u32_e64 v19, vcc, 0, v19, s[54:55]
	v_cmp_ge_u32_e64 s[54:55], v52, v18
	v_addc_co_u32_e64 v19, vcc, 0, v19, s[98:99]
	v_cmp_ge_u32_e64 s[98:99], v54, v18
	v_addc_co_u32_e64 v19, vcc, 0, v19, s[22:23]
	v_cmp_ge_u32_e64 s[22:23], v56, v18
	v_addc_co_u32_e64 v19, vcc, 0, v19, s[0:1]
	v_cmp_ge_u32_e64 s[0:1], v58, v18
	v_addc_co_u32_e64 v19, vcc, 0, v19, s[54:55]
	v_cmp_ge_u32_e64 s[54:55], v60, v18
	v_addc_co_u32_e64 v19, vcc, 0, v19, s[98:99]
	v_cmp_ge_u32_e64 s[98:99], v62, v18
	v_addc_co_u32_e64 v19, vcc, 0, v19, s[22:23]
	v_cmp_ge_u32_e64 s[22:23], v64, v18
	v_addc_co_u32_e64 v19, vcc, 0, v19, s[0:1]
	v_addc_co_u32_e64 v19, vcc, 0, v19, s[54:55]
	v_addc_co_u32_e64 v19, vcc, 0, v19, s[98:99]
	v_addc_co_u32_e64 v19, vcc, 0, v19, s[22:23]
	s_andn2_b64 vcc, exec, s[50:51]
	s_cbranch_vccz .LBB0_476
	s_branch .LBB0_477

; DI void a1_task(unsigned char* shm, const bf16_t* prm, const bf16_t* prt, unsigned* mask, int b, int qt, const int tid) {
;     ...
;             for (int jt = 0; jt < 8; ++jt) {
;                 if (jt < nheld) {
; #pragma unroll
;                     for (int i = 0; i < 16; ++i) c += (key[jt][i] >= cand) ? 1 : 0;
;                 }
.LBB0_470:
	v_cmp_ge_u32_e64 s[0:1], v166, v18
	v_cmp_ge_u32_e64 s[54:55], v159, v18
	v_cmp_ge_u32_e64 s[98:99], v161, v18
	v_cmp_ge_u32_e64 s[22:23], v163, v18
	v_addc_co_u32_e64 v19, vcc, 0, v19, s[0:1]
	v_cmp_ge_u32_e64 s[0:1], v165, v18
	v_addc_co_u32_e64 v19, vcc, 0, v19, s[54:55]
	v_cmp_ge_u32_e64 s[54:55], v169, v18
	v_addc_co_u32_e64 v19, vcc, 0, v19, s[98:99]
	v_cmp_ge_u32_e64 s[98:99], v171, v18
	v_addc_co_u32_e64 v19, vcc, 0, v19, s[22:23]
	v_cmp_ge_u32_e64 s[22:23], v173, v18
	v_addc_co_u32_e64 v19, vcc, 0, v19, s[0:1]
	v_cmp_ge_u32_e64 s[0:1], v167, v18
	v_addc_co_u32_e64 v19, vcc, 0, v19, s[54:55]
	v_cmp_ge_u32_e64 s[54:55], v158, v18
	v_addc_co_u32_e64 v19, vcc, 0, v19, s[98:99]
	v_cmp_ge_u32_e64 s[98:99], v160, v18
	v_addc_co_u32_e64 v19, vcc, 0, v19, s[22:23]
	v_cmp_ge_u32_e64 s[22:23], v162, v18
	v_addc_co_u32_e64 v19, vcc, 0, v19, s[0:1]
	v_cmp_ge_u32_e64 s[0:1], v164, v18
	v_addc_co_u32_e64 v19, vcc, 0, v19, s[54:55]
	v_cmp_ge_u32_e64 s[54:55], v168, v18
	v_addc_co_u32_e64 v19, vcc, 0, v19, s[98:99]
	v_cmp_ge_u32_e64 s[98:99], v170, v18
	v_addc_co_u32_e64 v19, vcc, 0, v19, s[22:23]
	v_cmp_ge_u32_e64 s[22:23], v172, v18
	v_addc_co_u32_e64 v19, vcc, 0, v19, s[0:1]
	v_addc_co_u32_e64 v19, vcc, 0, v19, s[54:55]
	v_addc_co_u32_e64 v19, vcc, 0, v19, s[98:99]
	v_addc_co_u32_e64 v19, vcc, 0, v19, s[22:23]
	s_andn2_b64 vcc, exec, s[8:9]
	s_cbranch_vccz .LBB0_464

; DI void a1_task(unsigned char* shm, const bf16_t* prm, const bf16_t* prt, unsigned* mask, int b, int qt, const int tid) {
;     ...
;             for (int jt = 0; jt < 8; ++jt) {
;                 if (jt < nheld) {
; #pragma unroll
;                     for (int i = 0; i < 16; ++i) c += (key[jt][i] >= cand) ? 1 : 0;
;                 }
.LBB0_472:
	v_cmp_ge_u32_e64 s[0:1], v191, v18
	v_cmp_ge_u32_e64 s[54:55], v193, v18
	v_cmp_ge_u32_e64 s[98:99], v212, v18
	v_cmp_ge_u32_e64 s[22:23], v214, v18
	v_addc_co_u32_e64 v19, vcc, 0, v19, s[0:1]
	v_cmp_ge_u32_e64 s[0:1], v216, v18
	v_addc_co_u32_e64 v19, vcc, 0, v19, s[54:55]
	v_cmp_ge_u32_e64 s[54:55], v218, v18
	v_addc_co_u32_e64 v19, vcc, 0, v19, s[98:99]
	v_cmp_ge_u32_e64 s[98:99], v220, v18
	v_addc_co_u32_e64 v19, vcc, 0, v19, s[22:23]
	v_cmp_ge_u32_e64 s[22:23], v222, v18
	v_addc_co_u32_e64 v19, vcc, 0, v19, s[0:1]
	v_cmp_ge_u32_e64 s[0:1], v190, v18
	v_addc_co_u32_e64 v19, vcc, 0, v19, s[54:55]
	v_cmp_ge_u32_e64 s[54:55], v192, v18
	v_addc_co_u32_e64 v19, vcc, 0, v19, s[98:99]
	v_cmp_ge_u32_e64 s[98:99], v211, v18
	v_addc_co_u32_e64 v19, vcc, 0, v19, s[22:23]
	v_cmp_ge_u32_e64 s[22:23], v213, v18
	v_addc_co_u32_e64 v19, vcc, 0, v19, s[0:1]
	v_cmp_ge_u32_e64 s[0:1], v215, v18
	v_addc_co_u32_e64 v19, vcc, 0, v19, s[54:55]
	v_cmp_ge_u32_e64 s[54:55], v217, v18
	v_addc_co_u32_e64 v19, vcc, 0, v19, s[98:99]
	v_cmp_ge_u32_e64 s[98:99], v219, v18
	v_addc_co_u32_e64 v19, vcc, 0, v19, s[22:23]
	v_cmp_ge_u32_e64 s[22:23], v221, v18
	v_addc_co_u32_e64 v19, vcc, 0, v19, s[0:1]
	v_addc_co_u32_e64 v19, vcc, 0, v19, s[54:55]
	v_addc_co_u32_e64 v19, vcc, 0, v19, s[98:99]
	v_addc_co_u32_e64 v19, vcc, 0, v19, s[22:23]
	s_andn2_b64 vcc, exec, s[44:45]
	s_cbranch_vccz .LBB0_466

; DI void a1_task(unsigned char* shm, const bf16_t* prm, const bf16_t* prt, unsigned* mask, int b, int qt, const int tid) {
;     ...
;             for (int jt = 0; jt < 8; ++jt) {
;                 if (jt < nheld) {
; #pragma unroll
;                     for (int i = 0; i < 16; ++i) c += (key[jt][i] >= cand) ? 1 : 0;
;                 }
.LBB0_474:
	v_cmp_ge_u32_e64 s[0:1], v87, v18
	v_cmp_ge_u32_e64 s[54:55], v89, v18
	v_cmp_ge_u32_e64 s[98:99], v95, v18
	v_cmp_ge_u32_e64 s[22:23], v97, v18
	v_addc_co_u32_e64 v19, vcc, 0, v19, s[0:1]
	v_cmp_ge_u32_e64 s[0:1], v244, v18
	v_addc_co_u32_e64 v19, vcc, 0, v19, s[54:55]
	v_cmp_ge_u32_e64 s[54:55], v246, v18
	v_addc_co_u32_e64 v19, vcc, 0, v19, s[98:99]
	v_cmp_ge_u32_e64 s[98:99], v248, v18
	v_addc_co_u32_e64 v19, vcc, 0, v19, s[22:23]
	v_cmp_ge_u32_e64 s[22:23], v250, v18
	v_addc_co_u32_e64 v19, vcc, 0, v19, s[0:1]
	v_cmp_ge_u32_e64 s[0:1], v86, v18
	v_addc_co_u32_e64 v19, vcc, 0, v19, s[54:55]
	v_cmp_ge_u32_e64 s[54:55], v88, v18
	v_addc_co_u32_e64 v19, vcc, 0, v19, s[98:99]
	v_cmp_ge_u32_e64 s[98:99], v94, v18
	v_addc_co_u32_e64 v19, vcc, 0, v19, s[22:23]
	v_cmp_ge_u32_e64 s[22:23], v96, v18
	v_addc_co_u32_e64 v19, vcc, 0, v19, s[0:1]
	v_cmp_ge_u32_e64 s[0:1], v231, v18
	v_addc_co_u32_e64 v19, vcc, 0, v19, s[54:55]
	v_cmp_ge_u32_e64 s[54:55], v245, v18
	v_addc_co_u32_e64 v19, vcc, 0, v19, s[98:99]
	v_cmp_ge_u32_e64 s[98:99], v247, v18
	v_addc_co_u32_e64 v19, vcc, 0, v19, s[22:23]
	v_cmp_ge_u32_e64 s[22:23], v249, v18
	v_addc_co_u32_e64 v19, vcc, 0, v19, s[0:1]
	v_addc_co_u32_e64 v19, vcc, 0, v19, s[54:55]
	v_addc_co_u32_e64 v19, vcc, 0, v19, s[98:99]
	v_addc_co_u32_e64 v19, vcc, 0, v19, s[22:23]
	s_andn2_b64 vcc, exec, s[48:49]
	s_cbranch_vccz .LBB0_468

; DI void a1_task(unsigned char* shm, const bf16_t* prm, const bf16_t* prt, unsigned* mask, int b, int qt, const int tid) {
;     ...
;             for (int jt = 0; jt < 8; ++jt) {
;                 if (jt < nheld) {
; #pragma unroll
;                     for (int i = 0; i < 16; ++i) c += (key[jt][i] >= cand) ? 1 : 0;
;                 }
.LBB0_476:
	v_cmp_ge_u32_e64 s[0:1], v35, v18
	v_cmp_ge_u32_e64 s[54:55], v17, v18
	v_cmp_ge_u32_e64 s[98:99], v15, v18
	v_cmp_ge_u32_e64 s[22:23], v13, v18
	v_addc_co_u32_e64 v19, vcc, 0, v19, s[0:1]
	v_cmp_ge_u32_e64 s[0:1], v11, v18
	v_addc_co_u32_e64 v19, vcc, 0, v19, s[54:55]
	v_cmp_ge_u32_e64 s[54:55], v9, v18
	v_addc_co_u32_e64 v19, vcc, 0, v19, s[98:99]
	v_cmp_ge_u32_e64 s[98:99], v7, v18
	v_addc_co_u32_e64 v19, vcc, 0, v19, s[22:23]
	v_cmp_ge_u32_e64 s[22:23], v5, v18
	v_addc_co_u32_e64 v19, vcc, 0, v19, s[0:1]
	v_cmp_ge_u32_e64 s[0:1], v34, v18
	v_addc_co_u32_e64 v19, vcc, 0, v19, s[54:55]
	v_cmp_ge_u32_e64 s[54:55], v16, v18
	v_addc_co_u32_e64 v19, vcc, 0, v19, s[98:99]
	v_cmp_ge_u32_e64 s[98:99], v14, v18
	v_addc_co_u32_e64 v19, vcc, 0, v19, s[22:23]
	v_cmp_ge_u32_e64 s[22:23], v12, v18
	v_addc_co_u32_e64 v19, vcc, 0, v19, s[0:1]
	v_cmp_ge_u32_e64 s[0:1], v10, v18
	v_addc_co_u32_e64 v19, vcc, 0, v19, s[54:55]
	v_cmp_ge_u32_e64 s[54:55], v8, v18
	v_addc_co_u32_e64 v19, vcc, 0, v19, s[98:99]
	v_cmp_ge_u32_e64 s[98:99], v6, v18
	v_addc_co_u32_e64 v19, vcc, 0, v19, s[22:23]
	v_cmp_ge_u32_e64 s[22:23], v4, v18
	v_addc_co_u32_e64 v19, vcc, 0, v19, s[0:1]
	v_addc_co_u32_e64 v19, vcc, 0, v19, s[54:55]
	v_addc_co_u32_e64 v19, vcc, 0, v19, s[98:99]
	v_addc_co_u32_e64 v19, vcc, 0, v19, s[22:23]
